# mode-0 K-loop: scalar address work of the heavy load segments (next-tile pointer selection, per-segment DMA bases) moved into the two light (DMA-only) segments; heavy segments keep only their M0 write
# speedup vs baseline: 1.0131x; 1.0074x over previous
; #define PG8_STAGE(bufoff, gbase, voff) do { _Pragma("unroll") for (int _i = 0; _i < 2; ++_i) \
;         __builtin_amdgcn_global_load_lds((const unsigned*)((const char*)(gbase) + (voff)[_i]), (LAS unsigned*)(lds + (bufoff) + ldsw + _i * 8192), 16, 0, 0); } while (0)
; #define PG8_LDA(dst, b, h) do { _Pragma("unroll") for (int m = 0; m < 4; ++m) _Pragma("unroll") for (int k = 0; k < 2; ++k) dst[m][k] = *(const LAS bf16x8*)(lds + PG8_SA(b, h) + aoff + m * 2048 + k * 1024); } while (0)
; #define PG8_LDB(dst, b, h) do { _Pragma("unroll") for (int n = 0; n < 2; ++n) _Pragma("unroll") for (int k = 0; k < 2; ++k) dst[n][k] = *(const LAS bf16x8*)(lds + PG8_SB(b, h) + boff + n * 2048 + k * 1024); } while (0)
; #define PG8_WAIT_V(n) asm volatile("s_waitcnt vmcnt(" #n ")" ::: "memory")
; #define PG8_WAIT_L(n) asm volatile("s_waitcnt lgkmcnt(" #n ")" ::: "memory")
; #define PG8_BAR __builtin_amdgcn_s_barrier()
; #define PG8_SCHED __builtin_amdgcn_sched_barrier(0)
; template <int MODE, class EpiT, class Sched>
; __device__ __forceinline__ void gemm_phase(LAS unsigned char* lds, const Gemm g, const Sched& S, const EpiT& E) {
;     ...
;         const bool has_next = S.next(ui + 1, nxt);
;         const char* nA = has_next ? (const char*)g.A + (size_t)nxt.pm * tstep : cA; const char* nB = has_next ? (const char*)g.Bt + (size_t)nxt.pn * tstep : cB;
;         for (int t = 0; t < nt; t += 2) {
;             const bool last = (t == nt - 2);
;             const char* a1 = cA + (size_t)(t + 1) * kstep;
;             const char* a2 = last ? nA : cA + (size_t)(t + 2) * kstep; const char* b2 = last ? nB : cB + (size_t)(t + 2) * kstep;
;             const char* a3 = a2 + kstep; const char* b3 = b2 + kstep;
;             PG8_LDB(B0, 0, 0); PG8_SCHED; PG8_LDA(At, 0, 0); PG8_STAGE(PG8_SA(1, 1), a1 + hstep, voffA);
;             PG8_WAIT_L(8); PG8_BAR; PG8_WAIT_L(0); PG8_MMA(0, 0, At, B0); PG8_BAR; PG8_SCHED;
;             PG8_LDB(B1, 0, 1); PG8_STAGE(PG8_SB(0, 0), b2, voffB);
;             PG8_BAR; PG8_WAIT_L(0); PG8_MMA(0, 1, At, B1); PG8_BAR;
;             PG8_LDA(At, 0, 1); PG8_STAGE(PG8_SA(0, 0), a2, voffA);
;             PG8_BAR; PG8_WAIT_L(0); PG8_MMA(1, 0, At, B0); PG8_BAR; PG8_SCHED;
;             PG8_STAGE(PG8_SB(0, 1), b2 + hstep, voffB);
;             PG8_WAIT_V(6); PG8_BAR; PG8_MMA(1, 1, At, B1); PG8_BAR;
.LBB0_331:
	s_mov_b32 s22, 0
	s_mov_b64 s[4:5], 0x100
	s_sub_u32 s58, s21, 0x80
	s_add_u32 s100, s12, s4
	s_addc_u32 s101, s13, s5
	s_add_u32 s44, s10, s4
	s_addc_u32 s45, s11, s5
	s_cmp_eq_u32 s55, 0
	s_cselect_b32 s39, s29, s101
	s_cselect_b32 s38, s28, s100
	s_cselect_b32 s45, s35, s45
	s_cselect_b32 s44, s34, s44
	s_add_u32 s98, s44, 0x80
	s_addc_u32 s99, s45, 0
	s_add_u32 s100, s100, s58
	s_addc_u32 s101, s101, 0
	s_mov_b32 s23, 0
	v_add_u32_e32 v145, 0x10000, v141
.LBB0_332:
	s_add_i32 s23, s23, 2
	ds_read_b128 v[146:149], v145
	ds_read_b128 v[150:153], v145 offset:1024
	ds_read_b128 v[154:157], v145 offset:2048
	ds_read_b128 v[158:161], v145 offset:3072
	s_add_i32 m0, s47, 0xc000
	ds_read_b128 v[162:165], v144
	ds_read_b128 v[166:169], v144 offset:1024
	ds_read_b128 v[170:173], v144 offset:2048
	ds_read_b128 v[174:177], v144 offset:3072
	ds_read_b128 v[182:185], v144 offset:4096
	ds_read_b128 v[186:189], v144 offset:5120
	ds_read_b128 v[190:193], v144 offset:6144
	global_load_lds_dwordx4 v0, s[100:101]
	s_add_i32 m0, s47, 0xe000
	ds_read_b128 v[194:197], v144 offset:7168
	global_load_lds_dwordx4 v130, s[100:101]
	s_waitcnt lgkmcnt(8)
	s_barrier
	s_waitcnt lgkmcnt(0)
	v_mfma_f32_16x16x32_bf16 v[126:129], v[146:149], v[162:165], v[126:129]
	v_mfma_f32_16x16x32_bf16 v[122:125], v[154:157], v[162:165], v[122:125]
	v_mfma_f32_16x16x32_bf16 v[118:121], v[146:149], v[170:173], v[118:121]
	v_mfma_f32_16x16x32_bf16 v[114:117], v[154:157], v[170:173], v[114:117]
	v_mfma_f32_16x16x32_bf16 v[110:113], v[146:149], v[182:185], v[110:113]
	v_mfma_f32_16x16x32_bf16 v[106:109], v[154:157], v[182:185], v[106:109]
	v_mfma_f32_16x16x32_bf16 v[102:105], v[146:149], v[190:193], v[102:105]
	v_mfma_f32_16x16x32_bf16 v[98:101], v[154:157], v[190:193], v[98:101]
	v_mfma_f32_16x16x32_bf16 v[126:129], v[150:153], v[166:169], v[126:129]
	v_mfma_f32_16x16x32_bf16 v[122:125], v[158:161], v[166:169], v[122:125]
	v_mfma_f32_16x16x32_bf16 v[118:121], v[150:153], v[174:177], v[118:121]
	v_mfma_f32_16x16x32_bf16 v[114:117], v[158:161], v[174:177], v[114:117]
	v_mfma_f32_16x16x32_bf16 v[110:113], v[150:153], v[186:189], v[110:113]
	v_mfma_f32_16x16x32_bf16 v[106:109], v[158:161], v[186:189], v[106:109]
	v_mfma_f32_16x16x32_bf16 v[102:105], v[150:153], v[194:197], v[102:105]
	v_mfma_f32_16x16x32_bf16 v[98:101], v[158:161], v[194:197], v[98:101]
	s_barrier
	s_add_i32 m0, s46, 0x10000
	ds_read_b128 v[220:223], v145 offset:16384
	ds_read_b128 v[224:227], v145 offset:17408
	ds_read_b128 v[228:231], v145 offset:18432
	global_load_lds_dwordx4 v0, s[44:45]
	s_add_i32 m0, s46, 0x12000
	ds_read_b128 v[232:235], v145 offset:19456
	global_load_lds_dwordx4 v130, s[44:45]
	s_barrier
	s_waitcnt lgkmcnt(0)
	v_mfma_f32_16x16x32_bf16 v[94:97], v[220:223], v[162:165], v[94:97]
	v_mfma_f32_16x16x32_bf16 v[90:93], v[228:231], v[162:165], v[90:93]
	v_mfma_f32_16x16x32_bf16 v[86:89], v[220:223], v[170:173], v[86:89]
	v_mfma_f32_16x16x32_bf16 v[82:85], v[228:231], v[170:173], v[82:85]
	v_mfma_f32_16x16x32_bf16 v[78:81], v[220:223], v[182:185], v[78:81]
	v_mfma_f32_16x16x32_bf16 v[74:77], v[228:231], v[182:185], v[74:77]
	v_mfma_f32_16x16x32_bf16 v[70:73], v[220:223], v[190:193], v[70:73]
	v_mfma_f32_16x16x32_bf16 v[66:69], v[228:231], v[190:193], v[66:69]
	v_mfma_f32_16x16x32_bf16 v[94:97], v[224:227], v[166:169], v[94:97]
	v_mfma_f32_16x16x32_bf16 v[90:93], v[232:235], v[166:169], v[90:93]
	v_mfma_f32_16x16x32_bf16 v[86:89], v[224:227], v[174:177], v[86:89]
	v_mfma_f32_16x16x32_bf16 v[82:85], v[232:235], v[174:177], v[82:85]
	v_mfma_f32_16x16x32_bf16 v[78:81], v[224:227], v[186:189], v[78:81]
	v_mfma_f32_16x16x32_bf16 v[74:77], v[232:235], v[186:189], v[74:77]
	v_mfma_f32_16x16x32_bf16 v[70:73], v[224:227], v[194:197], v[70:73]
	v_mfma_f32_16x16x32_bf16 v[66:69], v[232:235], v[194:197], v[66:69]
	s_barrier
	s_mov_b32 m0, s47
	ds_read_b128 v[162:165], v144 offset:16384
	ds_read_b128 v[166:169], v144 offset:17408
	ds_read_b128 v[170:173], v144 offset:18432
	ds_read_b128 v[174:177], v144 offset:19456
	ds_read_b128 v[182:185], v144 offset:20480
	ds_read_b128 v[186:189], v144 offset:21504
	ds_read_b128 v[190:193], v144 offset:22528
	global_load_lds_dwordx4 v0, s[38:39]
	s_mov_b32 m0, s50
	ds_read_b128 v[194:197], v144 offset:23552
	global_load_lds_dwordx4 v130, s[38:39]
	s_barrier
	s_waitcnt lgkmcnt(0)
	v_mfma_f32_16x16x32_bf16 v[62:65], v[146:149], v[162:165], v[62:65]
	v_mfma_f32_16x16x32_bf16 v[58:61], v[154:157], v[162:165], v[58:61]
	v_mfma_f32_16x16x32_bf16 v[54:57], v[146:149], v[170:173], v[54:57]
	v_mfma_f32_16x16x32_bf16 v[50:53], v[154:157], v[170:173], v[50:53]
	v_mfma_f32_16x16x32_bf16 v[46:49], v[146:149], v[182:185], v[46:49]
	v_mfma_f32_16x16x32_bf16 v[42:45], v[154:157], v[182:185], v[42:45]
	v_mfma_f32_16x16x32_bf16 v[38:41], v[146:149], v[190:193], v[38:41]
	v_mfma_f32_16x16x32_bf16 v[34:37], v[154:157], v[190:193], v[34:37]
	v_mfma_f32_16x16x32_bf16 v[62:65], v[150:153], v[166:169], v[62:65]
	v_mfma_f32_16x16x32_bf16 v[58:61], v[158:161], v[166:169], v[58:61]
	v_mfma_f32_16x16x32_bf16 v[54:57], v[150:153], v[174:177], v[54:57]
	v_mfma_f32_16x16x32_bf16 v[50:53], v[158:161], v[174:177], v[50:53]
	v_mfma_f32_16x16x32_bf16 v[46:49], v[150:153], v[186:189], v[46:49]
	v_mfma_f32_16x16x32_bf16 v[42:45], v[158:161], v[186:189], v[42:45]
	v_mfma_f32_16x16x32_bf16 v[38:41], v[150:153], v[194:197], v[38:41]
	v_mfma_f32_16x16x32_bf16 v[34:37], v[158:161], v[194:197], v[34:37]
	s_barrier
	s_add_u32 s100, s38, 0x80
	s_addc_u32 s101, s39, 0
	s_add_u32 s38, s38, s21
	s_addc_u32 s39, s39, 0
	s_add_u32 s44, s44, s21
	s_addc_u32 s45, s45, 0
	s_add_i32 m0, s46, 0x14000
	s_nop 0
	global_load_lds_dwordx4 v0, s[44:45]
	s_add_i32 m0, s46, 0x16000
	s_nop 0
	global_load_lds_dwordx4 v130, s[44:45]
	s_add_u32 s4, s4, 0x100
	s_addc_u32 s5, s5, 0
	s_waitcnt vmcnt(6)
	s_barrier
; #define PG8_STAGE(bufoff, gbase, voff) do { _Pragma("unroll") for (int _i = 0; _i < 2; ++_i) \
;         __builtin_amdgcn_global_load_lds((const unsigned*)((const char*)(gbase) + (voff)[_i]), (LAS unsigned*)(lds + (bufoff) + ldsw + _i * 8192), 16, 0, 0); } while (0)
; #define PG8_LDA(dst, b, h) do { _Pragma("unroll") for (int m = 0; m < 4; ++m) _Pragma("unroll") for (int k = 0; k < 2; ++k) dst[m][k] = *(const LAS bf16x8*)(lds + PG8_SA(b, h) + aoff + m * 2048 + k * 1024); } while (0)
; #define PG8_LDB(dst, b, h) do { _Pragma("unroll") for (int n = 0; n < 2; ++n) _Pragma("unroll") for (int k = 0; k < 2; ++k) dst[n][k] = *(const LAS bf16x8*)(lds + PG8_SB(b, h) + boff + n * 2048 + k * 1024); } while (0)
; #define PG8_MMA(ai, bj, At, Bt) do { __builtin_amdgcn_s_setprio(1); _Pragma("unroll") for (int m = 0; m < 4; ++m) _Pragma("unroll") for (int n = 0; n < 2; ++n) _Pragma("unroll") for (int k = 0; k < 2; ++k) \
;         acc[ai][bj][m][n] = __builtin_amdgcn_mfma_f32_16x16x32_bf16(Bt[n][k], At[m][k], acc[ai][bj][m][n], 0, 0, 0); __builtin_amdgcn_s_setprio(0); } while (0)
; template <int MODE, class EpiT, class Sched>
; __device__ __forceinline__ void gemm_phase(LAS unsigned char* lds, const Gemm g, const Sched& S, const EpiT& E) {
;     ...
;             PG8_LDB(B0, 0, 0); PG8_SCHED; PG8_LDA(At, 0, 0); PG8_STAGE(PG8_SA(1, 1), a1 + hstep, voffA);
;             PG8_WAIT_L(8); PG8_BAR; PG8_WAIT_L(0); PG8_MMA(0, 0, At, B0); PG8_BAR; PG8_SCHED;
;             PG8_LDB(B1, 0, 1); PG8_STAGE(PG8_SB(0, 0), b2, voffB);
;             PG8_BAR; PG8_WAIT_L(0); PG8_MMA(0, 1, At, B1); PG8_BAR;
;             PG8_LDA(At, 0, 1); PG8_STAGE(PG8_SA(0, 0), a2, voffA);
;             PG8_BAR; PG8_WAIT_L(0); PG8_MMA(1, 0, At, B0); PG8_BAR; PG8_SCHED;
;             PG8_STAGE(PG8_SB(0, 1), b2 + hstep, voffB);
;             PG8_WAIT_V(6); PG8_BAR; PG8_MMA(1, 1, At, B1); PG8_BAR;
;             PG8_LDB(B0, 1, 0); PG8_SCHED; PG8_LDA(At, 1, 0); PG8_STAGE(PG8_SA(0, 1), a2 + hstep, voffA);
;             PG8_WAIT_L(8); PG8_BAR; PG8_WAIT_L(0); PG8_MMA(0, 0, At, B0); PG8_BAR; PG8_SCHED;
;             PG8_LDB(B1, 1, 1); PG8_STAGE(PG8_SB(1, 0), b3, voffB);
;             PG8_BAR; PG8_WAIT_L(0); PG8_MMA(0, 1, At, B1); PG8_BAR;
;             PG8_LDA(At, 1, 1); PG8_STAGE(PG8_SA(1, 0), a3, voffA);
;             PG8_BAR; PG8_WAIT_L(0); PG8_MMA(1, 0, At, B0); PG8_BAR; PG8_SCHED;
	v_mfma_f32_16x16x32_bf16 v[30:33], v[220:223], v[162:165], v[30:33]
	v_mfma_f32_16x16x32_bf16 v[26:29], v[228:231], v[162:165], v[26:29]
	v_mfma_f32_16x16x32_bf16 v[22:25], v[220:223], v[170:173], v[22:25]
	v_mfma_f32_16x16x32_bf16 v[18:21], v[228:231], v[170:173], v[18:21]
	v_mfma_f32_16x16x32_bf16 v[14:17], v[220:223], v[182:185], v[14:17]
	v_mfma_f32_16x16x32_bf16 v[10:13], v[228:231], v[182:185], v[10:13]
	v_mfma_f32_16x16x32_bf16 v[6:9], v[220:223], v[190:193], v[6:9]
	v_mfma_f32_16x16x32_bf16 v[2:5], v[228:231], v[190:193], v[2:5]
	v_mfma_f32_16x16x32_bf16 v[30:33], v[224:227], v[166:169], v[30:33]
	v_mfma_f32_16x16x32_bf16 v[26:29], v[232:235], v[166:169], v[26:29]
	v_mfma_f32_16x16x32_bf16 v[22:25], v[224:227], v[174:177], v[22:25]
	v_mfma_f32_16x16x32_bf16 v[18:21], v[232:235], v[174:177], v[18:21]
	v_mfma_f32_16x16x32_bf16 v[14:17], v[224:227], v[186:189], v[14:17]
	v_mfma_f32_16x16x32_bf16 v[10:13], v[232:235], v[186:189], v[10:13]
	v_mfma_f32_16x16x32_bf16 v[6:9], v[224:227], v[194:197], v[6:9]
	v_mfma_f32_16x16x32_bf16 v[2:5], v[232:235], v[194:197], v[2:5]
	s_barrier
	ds_read_b128 v[146:149], v145 offset:32768
	ds_read_b128 v[150:153], v145 offset:33792
	ds_read_b128 v[154:157], v145 offset:34816
	ds_read_b128 v[158:161], v145 offset:35840
	s_mov_b32 m0, s51
	ds_read_b128 v[162:165], v144 offset:32768
	ds_read_b128 v[166:169], v144 offset:33792
	ds_read_b128 v[170:173], v144 offset:34816
	ds_read_b128 v[174:177], v144 offset:35840
	ds_read_b128 v[182:185], v144 offset:36864
	ds_read_b128 v[186:189], v144 offset:37888
	ds_read_b128 v[190:193], v144 offset:38912
	global_load_lds_dwordx4 v0, s[38:39]
	s_mov_b32 m0, s52
	ds_read_b128 v[194:197], v144 offset:39936
	global_load_lds_dwordx4 v130, s[38:39]
	s_waitcnt lgkmcnt(8)
	s_barrier
	s_waitcnt lgkmcnt(0)
	v_mfma_f32_16x16x32_bf16 v[126:129], v[146:149], v[162:165], v[126:129]
	v_mfma_f32_16x16x32_bf16 v[122:125], v[154:157], v[162:165], v[122:125]
	v_mfma_f32_16x16x32_bf16 v[118:121], v[146:149], v[170:173], v[118:121]
	v_mfma_f32_16x16x32_bf16 v[114:117], v[154:157], v[170:173], v[114:117]
	v_mfma_f32_16x16x32_bf16 v[110:113], v[146:149], v[182:185], v[110:113]
	v_mfma_f32_16x16x32_bf16 v[106:109], v[154:157], v[182:185], v[106:109]
	v_mfma_f32_16x16x32_bf16 v[102:105], v[146:149], v[190:193], v[102:105]
	v_mfma_f32_16x16x32_bf16 v[98:101], v[154:157], v[190:193], v[98:101]
	v_mfma_f32_16x16x32_bf16 v[126:129], v[150:153], v[166:169], v[126:129]
	v_mfma_f32_16x16x32_bf16 v[122:125], v[158:161], v[166:169], v[122:125]
	v_mfma_f32_16x16x32_bf16 v[118:121], v[150:153], v[174:177], v[118:121]
	v_mfma_f32_16x16x32_bf16 v[114:117], v[158:161], v[174:177], v[114:117]
	v_mfma_f32_16x16x32_bf16 v[110:113], v[150:153], v[186:189], v[110:113]
	v_mfma_f32_16x16x32_bf16 v[106:109], v[158:161], v[186:189], v[106:109]
	v_mfma_f32_16x16x32_bf16 v[102:105], v[150:153], v[194:197], v[102:105]
	v_mfma_f32_16x16x32_bf16 v[98:101], v[158:161], v[194:197], v[98:101]
	s_barrier
	s_add_i32 m0, s46, 0x18000
	ds_read_b128 v[220:223], v145 offset:49152
	ds_read_b128 v[224:227], v145 offset:50176
	ds_read_b128 v[228:231], v145 offset:51200
	global_load_lds_dwordx4 v0, s[98:99]
	s_add_i32 m0, s46, 0x1a000
	ds_read_b128 v[232:235], v145 offset:52224
	global_load_lds_dwordx4 v130, s[98:99]
	s_barrier
	s_waitcnt lgkmcnt(0)
	v_mfma_f32_16x16x32_bf16 v[94:97], v[220:223], v[162:165], v[94:97]
	v_mfma_f32_16x16x32_bf16 v[90:93], v[228:231], v[162:165], v[90:93]
	v_mfma_f32_16x16x32_bf16 v[86:89], v[220:223], v[170:173], v[86:89]
	v_mfma_f32_16x16x32_bf16 v[82:85], v[228:231], v[170:173], v[82:85]
	v_mfma_f32_16x16x32_bf16 v[78:81], v[220:223], v[182:185], v[78:81]
	v_mfma_f32_16x16x32_bf16 v[74:77], v[228:231], v[182:185], v[74:77]
	v_mfma_f32_16x16x32_bf16 v[70:73], v[220:223], v[190:193], v[70:73]
	v_mfma_f32_16x16x32_bf16 v[66:69], v[228:231], v[190:193], v[66:69]
	v_mfma_f32_16x16x32_bf16 v[94:97], v[224:227], v[166:169], v[94:97]
	v_mfma_f32_16x16x32_bf16 v[90:93], v[232:235], v[166:169], v[90:93]
	v_mfma_f32_16x16x32_bf16 v[86:89], v[224:227], v[174:177], v[86:89]
	v_mfma_f32_16x16x32_bf16 v[82:85], v[232:235], v[174:177], v[82:85]
	v_mfma_f32_16x16x32_bf16 v[78:81], v[224:227], v[186:189], v[78:81]
	v_mfma_f32_16x16x32_bf16 v[74:77], v[232:235], v[186:189], v[74:77]
	v_mfma_f32_16x16x32_bf16 v[70:73], v[224:227], v[194:197], v[70:73]
	v_mfma_f32_16x16x32_bf16 v[66:69], v[232:235], v[194:197], v[66:69]
	s_barrier
	s_mov_b32 m0, s53
	ds_read_b128 v[162:165], v144 offset:49152
	ds_read_b128 v[166:169], v144 offset:50176
	ds_read_b128 v[170:173], v144 offset:51200
	ds_read_b128 v[174:177], v144 offset:52224
	ds_read_b128 v[182:185], v144 offset:53248
	ds_read_b128 v[186:189], v144 offset:54272
	ds_read_b128 v[190:193], v144 offset:55296
	global_load_lds_dwordx4 v0, s[100:101]
	s_mov_b32 m0, s54
	ds_read_b128 v[194:197], v144 offset:56320
	global_load_lds_dwordx4 v130, s[100:101]
	s_barrier
	s_waitcnt lgkmcnt(0)
	v_mfma_f32_16x16x32_bf16 v[62:65], v[146:149], v[162:165], v[62:65]
	v_mfma_f32_16x16x32_bf16 v[58:61], v[154:157], v[162:165], v[58:61]
	v_mfma_f32_16x16x32_bf16 v[54:57], v[146:149], v[170:173], v[54:57]
	v_mfma_f32_16x16x32_bf16 v[50:53], v[154:157], v[170:173], v[50:53]
	v_mfma_f32_16x16x32_bf16 v[46:49], v[146:149], v[182:185], v[46:49]
	v_mfma_f32_16x16x32_bf16 v[42:45], v[154:157], v[182:185], v[42:45]
	v_mfma_f32_16x16x32_bf16 v[38:41], v[146:149], v[190:193], v[38:41]
	v_mfma_f32_16x16x32_bf16 v[34:37], v[154:157], v[190:193], v[34:37]
	v_mfma_f32_16x16x32_bf16 v[62:65], v[150:153], v[166:169], v[62:65]
	v_mfma_f32_16x16x32_bf16 v[58:61], v[158:161], v[166:169], v[58:61]
	v_mfma_f32_16x16x32_bf16 v[54:57], v[150:153], v[174:177], v[54:57]
	v_mfma_f32_16x16x32_bf16 v[50:53], v[158:161], v[174:177], v[50:53]
	v_mfma_f32_16x16x32_bf16 v[46:49], v[150:153], v[186:189], v[46:49]
	v_mfma_f32_16x16x32_bf16 v[42:45], v[158:161], v[186:189], v[42:45]
	v_mfma_f32_16x16x32_bf16 v[38:41], v[150:153], v[194:197], v[38:41]
	v_mfma_f32_16x16x32_bf16 v[34:37], v[158:161], v[194:197], v[34:37]
	s_barrier
; __device__ __forceinline__ unsigned pk2(float lo, float hi) { unsigned r; asm volatile("v_cvt_pk_bf16_f32 %0, %1, %2" : "=v"(r) : "v"(lo), "v"(hi)); return r; }
; __device__ __forceinline__ float siluf_(float x) { return x * __builtin_amdgcn_rcpf(1.0f + __expf(-x)); }
; #define PG8_WAIT_V(n) asm volatile("s_waitcnt vmcnt(" #n ")" ::: "memory")
; #define PG8_WAIT_L(n) asm volatile("s_waitcnt lgkmcnt(" #n ")" ::: "memory")
; #define PG8_BAR __builtin_amdgcn_s_barrier()
;     template <int mode> __device__ __forceinline__ void run(const f32x4 (&acc)[2][2][4][2], const Unit& u, int wr, int wc, int fr, int fq, const LAS float* sc) const {
;     ...
;         if (mode == 0) {
;             const int col0 = u.pn * HALF + wc * 32 + 8 * fq;
; #pragma unroll
;             for (int ai = 0; ai < 2; ++ai)
; #pragma unroll
;                 for (int m = 0; m < 4; ++m) {
;                     const int row = row0 + ai * HALF + m * 16;
;                     const float s = sc[ai * HALF + wr * 64 + m * 16 + fr];
;                     const f32x4 g0 = acc[ai][0][m][0] * s, u0 = acc[ai][1][m][0] * s, g1 = acc[ai][0][m][1] * s, u1 = acc[ai][1][m][1] * s;
;                     u32x4 w;
;                     w.x = pk2(siluf_(g0[0]) * u0[0], siluf_(g0[1]) * u0[1]); w.y = pk2(siluf_(g0[2]) * u0[2], siluf_(g0[3]) * u0[3]);
;                     w.z = pk2(siluf_(g1[0]) * u1[0], siluf_(g1[1]) * u1[1]); w.w = pk2(siluf_(g1[2]) * u1[2], siluf_(g1[3]) * u1[3]);
;                     *(u32x4*)(ob + (size_t)row * FF + col0) = w;
;                 }
; template <int MODE, class EpiT, class Sched>
; __device__ __forceinline__ void gemm_phase(LAS unsigned char* lds, const Gemm g, const Sched& S, const EpiT& E) {
;     ...
;             PG8_WAIT_V(6); PG8_BAR; PG8_MMA(1, 1, At, B1); PG8_BAR;
;             PG8_LDB(B0, 1, 0); PG8_SCHED; PG8_LDA(At, 1, 0); PG8_STAGE(PG8_SA(0, 1), a2 + hstep, voffA);
;             PG8_WAIT_L(8); PG8_BAR; PG8_WAIT_L(0); PG8_MMA(0, 0, At, B0); PG8_BAR; PG8_SCHED;
;             PG8_LDB(B1, 1, 1); PG8_STAGE(PG8_SB(1, 0), b3, voffB);
;             PG8_BAR; PG8_WAIT_L(0); PG8_MMA(0, 1, At, B1); PG8_BAR;
;             PG8_LDA(At, 1, 1); PG8_STAGE(PG8_SA(1, 0), a3, voffA);
;             PG8_BAR; PG8_WAIT_L(0); PG8_MMA(1, 0, At, B0); PG8_BAR; PG8_SCHED;
;             PG8_STAGE(PG8_SB(1, 1), b3 + hstep, voffB);
;             PG8_WAIT_V(6); PG8_BAR; PG8_MMA(1, 1, At, B1); PG8_BAR;
	s_add_u32 s98, s44, 0x80
	s_addc_u32 s99, s45, 0
	s_add_i32 m0, s46, 0x1c000
	s_nop 0
	global_load_lds_dwordx4 v0, s[98:99]
	s_add_i32 m0, s46, 0x1e000
	s_nop 0
	global_load_lds_dwordx4 v130, s[98:99]
	s_add_u32 s100, s12, s4
	s_addc_u32 s101, s13, s5
	s_add_u32 s44, s10, s4
	s_addc_u32 s45, s11, s5
	s_cmp_eq_u32 s55, s23
	s_cselect_b32 s39, s29, s101
	s_cselect_b32 s38, s28, s100
	s_cselect_b32 s45, s35, s45
	s_cselect_b32 s44, s34, s44
	s_add_u32 s98, s44, 0x80
	s_addc_u32 s99, s45, 0
	s_add_u32 s100, s100, s58
	s_addc_u32 s101, s101, 0
	s_waitcnt vmcnt(6)
	s_barrier
	v_mfma_f32_16x16x32_bf16 v[30:33], v[220:223], v[162:165], v[30:33]
	v_mfma_f32_16x16x32_bf16 v[26:29], v[228:231], v[162:165], v[26:29]
	v_mfma_f32_16x16x32_bf16 v[22:25], v[220:223], v[170:173], v[22:25]
	v_mfma_f32_16x16x32_bf16 v[18:21], v[228:231], v[170:173], v[18:21]
	v_mfma_f32_16x16x32_bf16 v[14:17], v[220:223], v[182:185], v[14:17]
	v_mfma_f32_16x16x32_bf16 v[10:13], v[228:231], v[182:185], v[10:13]
	v_mfma_f32_16x16x32_bf16 v[6:9], v[220:223], v[190:193], v[6:9]
	v_mfma_f32_16x16x32_bf16 v[2:5], v[228:231], v[190:193], v[2:5]
	v_mfma_f32_16x16x32_bf16 v[30:33], v[224:227], v[166:169], v[30:33]
	v_mfma_f32_16x16x32_bf16 v[26:29], v[232:235], v[166:169], v[26:29]
	v_mfma_f32_16x16x32_bf16 v[22:25], v[224:227], v[174:177], v[22:25]
	v_mfma_f32_16x16x32_bf16 v[18:21], v[232:235], v[174:177], v[18:21]
	v_mfma_f32_16x16x32_bf16 v[14:17], v[224:227], v[186:189], v[14:17]
	v_mfma_f32_16x16x32_bf16 v[10:13], v[232:235], v[186:189], v[10:13]
	v_mfma_f32_16x16x32_bf16 v[6:9], v[224:227], v[194:197], v[6:9]
	v_mfma_f32_16x16x32_bf16 v[2:5], v[232:235], v[194:197], v[2:5]
	s_barrier
	s_cmp_ge_u32 s23, s16
	s_mov_b32 s22, s23
	s_cbranch_scc0 .LBB0_332
	v_lshl_add_u32 v145, s57, 10, v142
	ds_read_b32 v136, v145
	v_lshl_or_b32 v138, s8, 7, v143
	v_lshl_add_u32 v146, s9, 8, v140
	v_ashrrev_i32_e32 v139, 31, v138
	v_lshlrev_b64 v[138:139], 1, v[138:139]
	s_waitcnt lgkmcnt(0)
	v_pk_mul_f32 v[148:149], v[126:127], v[136:137] op_sel_hi:[1,0]
	v_pk_mul_f32 v[154:155], v[94:95], v[136:137] op_sel_hi:[1,0]
	v_mul_f32_e32 v147, 0xbfb8aa3b, v148
	v_exp_f32_e32 v147, v147
	v_pk_mul_f32 v[150:151], v[128:129], v[136:137] op_sel_hi:[1,0]
	v_pk_mul_f32 v[152:153], v[96:97], v[136:137] op_sel_hi:[1,0]
	v_pk_mul_f32 v[158:159], v[122:123], v[136:137] op_sel_hi:[1,0]
	v_add_f32_e32 v147, 1.0, v147
	v_rcp_f32_e32 v147, v147
	v_pk_mul_f32 v[156:157], v[124:125], v[136:137] op_sel_hi:[1,0]
	v_pk_mul_f32 v[160:161], v[92:93], v[136:137] op_sel_hi:[1,0]
	v_pk_mul_f32 v[136:137], v[90:91], v[136:137] op_sel_hi:[1,0]
	v_mul_f32_e32 v147, v148, v147
	v_mul_f32_e32 v148, 0xbfb8aa3b, v149
	v_exp_f32_e32 v148, v148
	v_mul_f32_e32 v147, v154, v147
	s_and_b64 vcc, exec, s[42:43]
	v_add_f32_e32 v148, 1.0, v148
	v_rcp_f32_e32 v148, v148
	s_nop 0
	v_mul_f32_e32 v148, v149, v148
	v_mul_f32_e32 v148, v155, v148
	v_cvt_pk_bf16_f32 v148, v147, v148
	v_mul_f32_e32 v147, 0xbfb8aa3b, v150
	v_mul_f32_e32 v149, 0xbfb8aa3b, v151
	v_exp_f32_e32 v147, v147
	v_exp_f32_e32 v149, v149
	v_add_f32_e32 v147, 1.0, v147
	v_add_f32_e32 v149, 1.0, v149
	v_rcp_f32_e32 v147, v147
	v_rcp_f32_e32 v149, v149
	v_mul_f32_e32 v147, v150, v147
	v_mul_f32_e32 v149, v151, v149
	v_mul_f32_e32 v147, v152, v147
	v_mul_f32_e32 v149, v153, v149
	v_cvt_pk_bf16_f32 v149, v147, v149
	v_mul_f32_e32 v147, 0xbfb8aa3b, v158
	v_exp_f32_e32 v147, v147
	s_nop 0
	v_add_f32_e32 v147, 1.0, v147
	v_rcp_f32_e32 v147, v147
	s_nop 0
	v_mul_f32_e32 v147, v158, v147
	v_mul_f32_e32 v136, v136, v147
	v_mul_f32_e32 v147, 0xbfb8aa3b, v159
	v_exp_f32_e32 v147, v147
	s_nop 0
	v_add_f32_e32 v147, 1.0, v147
	v_rcp_f32_e32 v147, v147
	s_nop 0
	v_mul_f32_e32 v147, v159, v147
	v_mul_f32_e32 v137, v137, v147
	v_cvt_pk_bf16_f32 v150, v136, v137
	v_mul_f32_e32 v136, 0xbfb8aa3b, v156
	v_mul_f32_e32 v137, 0xbfb8aa3b, v157
	v_exp_f32_e32 v136, v136
	v_exp_f32_e32 v137, v137
	v_or_b32_e32 v147, 16, v146
	v_add_f32_e32 v136, 1.0, v136
	v_add_f32_e32 v137, 1.0, v137
	v_rcp_f32_e32 v136, v136
	v_rcp_f32_e32 v137, v137
	v_mul_f32_e32 v136, v156, v136
	v_mul_f32_e32 v137, v157, v137
	v_mul_f32_e32 v136, v160, v136
	v_mul_f32_e32 v137, v161, v137
	v_cvt_pk_bf16_f32 v151, v136, v137
	v_mov_b64_e32 v[136:137], s[6:7]
	v_mad_i64_i32 v[152:153], s[4:5], v146, s33, v[136:137]
	v_lshl_add_u64 v[152:153], v[152:153], 0, v[138:139]
	global_store_dwordx4 v[152:153], v[148:151], off
	ds_read_b32 v148, v145 offset:64
	s_waitcnt lgkmcnt(0)
; __device__ __forceinline__ unsigned pk2(float lo, float hi) { unsigned r; asm volatile("v_cvt_pk_bf16_f32 %0, %1, %2" : "=v"(r) : "v"(lo), "v"(hi)); return r; }
; __device__ __forceinline__ float siluf_(float x) { return x * __builtin_amdgcn_rcpf(1.0f + __expf(-x)); }
;     template <int mode> __device__ __forceinline__ void run(const f32x4 (&acc)[2][2][4][2], const Unit& u, int wr, int wc, int fr, int fq, const LAS float* sc) const {
;     ...
; #pragma unroll
;             for (int ai = 0; ai < 2; ++ai)
; #pragma unroll
;                 for (int m = 0; m < 4; ++m) {
;                     const int row = row0 + ai * HALF + m * 16;
;                     const float s = sc[ai * HALF + wr * 64 + m * 16 + fr];
;                     const f32x4 g0 = acc[ai][0][m][0] * s, u0 = acc[ai][1][m][0] * s, g1 = acc[ai][0][m][1] * s, u1 = acc[ai][1][m][1] * s;
;                     u32x4 w;
;                     w.x = pk2(siluf_(g0[0]) * u0[0], siluf_(g0[1]) * u0[1]); w.y = pk2(siluf_(g0[2]) * u0[2], siluf_(g0[3]) * u0[3]);
;                     w.z = pk2(siluf_(g1[0]) * u1[0], siluf_(g1[1]) * u1[1]); w.w = pk2(siluf_(g1[2]) * u1[2], siluf_(g1[3]) * u1[3]);
;                     *(u32x4*)(ob + (size_t)row * FF + col0) = w;
;                 }
	v_pk_mul_f32 v[152:153], v[118:119], v[148:149] op_sel_hi:[1,0]
	v_pk_mul_f32 v[150:151], v[120:121], v[148:149] op_sel_hi:[1,0]
	v_pk_mul_f32 v[154:155], v[88:89], v[148:149] op_sel_hi:[1,0]
	v_pk_mul_f32 v[156:157], v[86:87], v[148:149] op_sel_hi:[1,0]
	v_pk_mul_f32 v[158:159], v[116:117], v[148:149] op_sel_hi:[1,0]
	v_pk_mul_f32 v[160:161], v[114:115], v[148:149] op_sel_hi:[1,0]
	v_pk_mul_f32 v[162:163], v[84:85], v[148:149] op_sel_hi:[1,0]
	v_pk_mul_f32 v[164:165], v[82:83], v[148:149] op_sel_hi:[1,0]
	v_mul_f32_e32 v148, 0xbfb8aa3b, v152
	v_mul_f32_e32 v149, 0xbfb8aa3b, v153
	v_exp_f32_e32 v148, v148
	v_exp_f32_e32 v149, v149
	v_add_f32_e32 v148, 1.0, v148
	v_add_f32_e32 v149, 1.0, v149
	v_rcp_f32_e32 v148, v148
	v_rcp_f32_e32 v149, v149
	v_mul_f32_e32 v148, v152, v148
	v_mul_f32_e32 v149, v153, v149
	v_mul_f32_e32 v148, v156, v148
	v_mul_f32_e32 v149, v157, v149
	v_cvt_pk_bf16_f32 v148, v148, v149
	v_mul_f32_e32 v149, 0xbfb8aa3b, v150
	v_exp_f32_e32 v149, v149
	v_mul_f32_e32 v152, 0xbfb8aa3b, v159
	v_exp_f32_e32 v152, v152
	v_add_f32_e32 v149, 1.0, v149
	v_rcp_f32_e32 v149, v149
	v_add_f32_e32 v152, 1.0, v152
	v_rcp_f32_e32 v152, v152
	v_mul_f32_e32 v149, v150, v149
	v_mul_f32_e32 v150, 0xbfb8aa3b, v151
	v_exp_f32_e32 v150, v150
	v_mul_f32_e32 v149, v154, v149
	v_mul_f32_e32 v152, v159, v152
	v_mul_f32_e32 v152, v163, v152
	v_add_f32_e32 v150, 1.0, v150
	v_rcp_f32_e32 v150, v150
	s_nop 0
	v_mul_f32_e32 v150, v151, v150
	v_mul_f32_e32 v150, v155, v150
	v_cvt_pk_bf16_f32 v149, v149, v150
	v_mul_f32_e32 v150, 0xbfb8aa3b, v160
	v_mul_f32_e32 v151, 0xbfb8aa3b, v161
	v_exp_f32_e32 v150, v150
	v_exp_f32_e32 v151, v151
	v_add_f32_e32 v150, 1.0, v150
	v_add_f32_e32 v151, 1.0, v151
	v_rcp_f32_e32 v150, v150
	v_rcp_f32_e32 v151, v151
	v_mul_f32_e32 v150, v160, v150
	v_mul_f32_e32 v151, v161, v151
	v_mul_f32_e32 v150, v164, v150
	v_mul_f32_e32 v151, v165, v151
	v_cvt_pk_bf16_f32 v150, v150, v151
	v_mul_f32_e32 v151, 0xbfb8aa3b, v158
	v_exp_f32_e32 v151, v151
	s_nop 0
	v_add_f32_e32 v151, 1.0, v151
	v_rcp_f32_e32 v151, v151
	s_nop 0
	v_mul_f32_e32 v151, v158, v151
	v_mul_f32_e32 v151, v162, v151
	v_cvt_pk_bf16_f32 v151, v151, v152
	v_mad_i64_i32 v[152:153], s[4:5], v147, s33, v[136:137]
	v_lshl_add_u64 v[152:153], v[152:153], 0, v[138:139]
	global_store_dwordx4 v[152:153], v[148:151], off
	ds_read_b32 v148, v145 offset:128
	v_or_b32_e32 v147, 32, v146
	s_waitcnt lgkmcnt(0)
	v_pk_mul_f32 v[152:153], v[110:111], v[148:149] op_sel_hi:[1,0]
	v_pk_mul_f32 v[150:151], v[112:113], v[148:149] op_sel_hi:[1,0]
	v_pk_mul_f32 v[154:155], v[80:81], v[148:149] op_sel_hi:[1,0]
	v_pk_mul_f32 v[156:157], v[78:79], v[148:149] op_sel_hi:[1,0]
	v_pk_mul_f32 v[158:159], v[108:109], v[148:149] op_sel_hi:[1,0]
	v_pk_mul_f32 v[160:161], v[106:107], v[148:149] op_sel_hi:[1,0]
	v_pk_mul_f32 v[162:163], v[76:77], v[148:149] op_sel_hi:[1,0]
	v_pk_mul_f32 v[164:165], v[74:75], v[148:149] op_sel_hi:[1,0]
	v_mul_f32_e32 v148, 0xbfb8aa3b, v152
	v_mul_f32_e32 v149, 0xbfb8aa3b, v153
	v_exp_f32_e32 v148, v148
	v_exp_f32_e32 v149, v149
	v_add_f32_e32 v148, 1.0, v148
	v_add_f32_e32 v149, 1.0, v149
	v_rcp_f32_e32 v148, v148
	v_rcp_f32_e32 v149, v149
	v_mul_f32_e32 v148, v152, v148
	v_mul_f32_e32 v149, v153, v149
	v_mul_f32_e32 v148, v156, v148
	v_mul_f32_e32 v149, v157, v149
	v_cvt_pk_bf16_f32 v148, v148, v149
	v_mul_f32_e32 v149, 0xbfb8aa3b, v150
	v_exp_f32_e32 v149, v149
	v_mul_f32_e32 v152, 0xbfb8aa3b, v159
	v_exp_f32_e32 v152, v152
	v_add_f32_e32 v149, 1.0, v149
	v_rcp_f32_e32 v149, v149
	v_add_f32_e32 v152, 1.0, v152
	v_rcp_f32_e32 v152, v152
	v_mul_f32_e32 v149, v150, v149
	v_mul_f32_e32 v150, 0xbfb8aa3b, v151
	v_exp_f32_e32 v150, v150
	v_mul_f32_e32 v149, v154, v149
	v_mul_f32_e32 v152, v159, v152
	v_mul_f32_e32 v152, v163, v152
	v_add_f32_e32 v150, 1.0, v150
	v_rcp_f32_e32 v150, v150
	s_nop 0
	v_mul_f32_e32 v150, v151, v150
	v_mul_f32_e32 v150, v155, v150
	v_cvt_pk_bf16_f32 v149, v149, v150
	v_mul_f32_e32 v150, 0xbfb8aa3b, v160
	v_mul_f32_e32 v151, 0xbfb8aa3b, v161
	v_exp_f32_e32 v150, v150
	v_exp_f32_e32 v151, v151
	v_add_f32_e32 v150, 1.0, v150
	v_add_f32_e32 v151, 1.0, v151
	v_rcp_f32_e32 v150, v150
	v_rcp_f32_e32 v151, v151
	v_mul_f32_e32 v150, v160, v150
	v_mul_f32_e32 v151, v161, v151
	v_mul_f32_e32 v150, v164, v150
	v_mul_f32_e32 v151, v165, v151
	v_cvt_pk_bf16_f32 v150, v150, v151
	v_mul_f32_e32 v151, 0xbfb8aa3b, v158
	v_exp_f32_e32 v151, v151
	s_nop 0
	v_add_f32_e32 v151, 1.0, v151
	v_rcp_f32_e32 v151, v151
	s_nop 0
	v_mul_f32_e32 v151, v158, v151
	v_mul_f32_e32 v151, v162, v151
	v_cvt_pk_bf16_f32 v151, v151, v152
	v_mad_i64_i32 v[152:153], s[4:5], v147, s33, v[136:137]
	v_lshl_add_u64 v[152:153], v[152:153], 0, v[138:139]
	global_store_dwordx4 v[152:153], v[148:151], off
	ds_read_b32 v148, v145 offset:192
	v_or_b32_e32 v147, 48, v146
	s_waitcnt lgkmcnt(0)
; __device__ __forceinline__ unsigned pk2(float lo, float hi) { unsigned r; asm volatile("v_cvt_pk_bf16_f32 %0, %1, %2" : "=v"(r) : "v"(lo), "v"(hi)); return r; }
; __device__ __forceinline__ float siluf_(float x) { return x * __builtin_amdgcn_rcpf(1.0f + __expf(-x)); }
;     template <int mode> __device__ __forceinline__ void run(const f32x4 (&acc)[2][2][4][2], const Unit& u, int wr, int wc, int fr, int fq, const LAS float* sc) const {
;     ...
; #pragma unroll
;             for (int ai = 0; ai < 2; ++ai)
; #pragma unroll
;                 for (int m = 0; m < 4; ++m) {
;                     const int row = row0 + ai * HALF + m * 16;
;                     const float s = sc[ai * HALF + wr * 64 + m * 16 + fr];
;                     const f32x4 g0 = acc[ai][0][m][0] * s, u0 = acc[ai][1][m][0] * s, g1 = acc[ai][0][m][1] * s, u1 = acc[ai][1][m][1] * s;
;                     u32x4 w;
;                     w.x = pk2(siluf_(g0[0]) * u0[0], siluf_(g0[1]) * u0[1]); w.y = pk2(siluf_(g0[2]) * u0[2], siluf_(g0[3]) * u0[3]);
;                     w.z = pk2(siluf_(g1[0]) * u1[0], siluf_(g1[1]) * u1[1]); w.w = pk2(siluf_(g1[2]) * u1[2], siluf_(g1[3]) * u1[3]);
;                     *(u32x4*)(ob + (size_t)row * FF + col0) = w;
;                 }
	v_pk_mul_f32 v[152:153], v[102:103], v[148:149] op_sel_hi:[1,0]
	v_pk_mul_f32 v[150:151], v[104:105], v[148:149] op_sel_hi:[1,0]
	v_pk_mul_f32 v[154:155], v[72:73], v[148:149] op_sel_hi:[1,0]
	v_pk_mul_f32 v[156:157], v[70:71], v[148:149] op_sel_hi:[1,0]
	v_pk_mul_f32 v[158:159], v[100:101], v[148:149] op_sel_hi:[1,0]
	v_pk_mul_f32 v[160:161], v[98:99], v[148:149] op_sel_hi:[1,0]
	v_pk_mul_f32 v[162:163], v[68:69], v[148:149] op_sel_hi:[1,0]
	v_pk_mul_f32 v[164:165], v[66:67], v[148:149] op_sel_hi:[1,0]
	v_mul_f32_e32 v148, 0xbfb8aa3b, v152
	v_mul_f32_e32 v149, 0xbfb8aa3b, v153
	v_exp_f32_e32 v148, v148
	v_exp_f32_e32 v149, v149
	v_add_f32_e32 v148, 1.0, v148
	v_add_f32_e32 v149, 1.0, v149
	v_rcp_f32_e32 v148, v148
	v_rcp_f32_e32 v149, v149
	v_mul_f32_e32 v148, v152, v148
	v_mul_f32_e32 v149, v153, v149
	v_mul_f32_e32 v148, v156, v148
	v_mul_f32_e32 v149, v157, v149
	v_cvt_pk_bf16_f32 v148, v148, v149
	v_mul_f32_e32 v149, 0xbfb8aa3b, v150
	v_exp_f32_e32 v149, v149
	v_mul_f32_e32 v152, 0xbfb8aa3b, v159
	v_exp_f32_e32 v152, v152
	v_add_f32_e32 v149, 1.0, v149
	v_rcp_f32_e32 v149, v149
	v_add_f32_e32 v152, 1.0, v152
	v_rcp_f32_e32 v152, v152
	v_mul_f32_e32 v149, v150, v149
	v_mul_f32_e32 v150, 0xbfb8aa3b, v151
	v_exp_f32_e32 v150, v150
	v_mul_f32_e32 v149, v154, v149
	v_mul_f32_e32 v152, v159, v152
	v_mul_f32_e32 v152, v163, v152
	v_add_f32_e32 v150, 1.0, v150
	v_rcp_f32_e32 v150, v150
	s_nop 0
	v_mul_f32_e32 v150, v151, v150
	v_mul_f32_e32 v150, v155, v150
	v_cvt_pk_bf16_f32 v149, v149, v150
	v_mul_f32_e32 v150, 0xbfb8aa3b, v160
	v_mul_f32_e32 v151, 0xbfb8aa3b, v161
	v_exp_f32_e32 v150, v150
	v_exp_f32_e32 v151, v151
	v_add_f32_e32 v150, 1.0, v150
	v_add_f32_e32 v151, 1.0, v151
	v_rcp_f32_e32 v150, v150
	v_rcp_f32_e32 v151, v151
	v_mul_f32_e32 v150, v160, v150
	v_mul_f32_e32 v151, v161, v151
	v_mul_f32_e32 v150, v164, v150
	v_mul_f32_e32 v151, v165, v151
	v_cvt_pk_bf16_f32 v150, v150, v151
	v_mul_f32_e32 v151, 0xbfb8aa3b, v158
	v_exp_f32_e32 v151, v151
	s_nop 0
	v_add_f32_e32 v151, 1.0, v151
	v_rcp_f32_e32 v151, v151
	s_nop 0
	v_mul_f32_e32 v151, v158, v151
	v_mul_f32_e32 v151, v162, v151
	v_cvt_pk_bf16_f32 v151, v151, v152
	v_mad_i64_i32 v[152:153], s[4:5], v147, s33, v[136:137]
	v_lshl_add_u64 v[152:153], v[152:153], 0, v[138:139]
	global_store_dwordx4 v[152:153], v[148:151], off
	ds_read_b32 v148, v145 offset:512
	v_add_u32_e32 v147, 0x80, v146
	s_waitcnt lgkmcnt(0)
	v_pk_mul_f32 v[152:153], v[62:63], v[148:149] op_sel_hi:[1,0]
	v_pk_mul_f32 v[150:151], v[64:65], v[148:149] op_sel_hi:[1,0]
	v_pk_mul_f32 v[154:155], v[32:33], v[148:149] op_sel_hi:[1,0]
	v_pk_mul_f32 v[156:157], v[30:31], v[148:149] op_sel_hi:[1,0]
	v_pk_mul_f32 v[158:159], v[60:61], v[148:149] op_sel_hi:[1,0]
	v_pk_mul_f32 v[160:161], v[58:59], v[148:149] op_sel_hi:[1,0]
	v_pk_mul_f32 v[162:163], v[28:29], v[148:149] op_sel_hi:[1,0]
	v_pk_mul_f32 v[164:165], v[26:27], v[148:149] op_sel_hi:[1,0]
	v_mul_f32_e32 v148, 0xbfb8aa3b, v152
	v_mul_f32_e32 v149, 0xbfb8aa3b, v153
	v_exp_f32_e32 v148, v148
	v_exp_f32_e32 v149, v149
	v_add_f32_e32 v148, 1.0, v148
	v_add_f32_e32 v149, 1.0, v149
	v_rcp_f32_e32 v148, v148
	v_rcp_f32_e32 v149, v149
	v_mul_f32_e32 v148, v152, v148
	v_mul_f32_e32 v149, v153, v149
	v_mul_f32_e32 v148, v156, v148
	v_mul_f32_e32 v149, v157, v149
	v_cvt_pk_bf16_f32 v148, v148, v149
	v_mul_f32_e32 v149, 0xbfb8aa3b, v150
	v_exp_f32_e32 v149, v149
	v_mul_f32_e32 v152, 0xbfb8aa3b, v159
	v_exp_f32_e32 v152, v152
	v_add_f32_e32 v149, 1.0, v149
	v_rcp_f32_e32 v149, v149
	v_add_f32_e32 v152, 1.0, v152
	v_rcp_f32_e32 v152, v152
	v_mul_f32_e32 v149, v150, v149
	v_mul_f32_e32 v150, 0xbfb8aa3b, v151
	v_exp_f32_e32 v150, v150
	v_mul_f32_e32 v149, v154, v149
	v_mul_f32_e32 v152, v159, v152
	v_mul_f32_e32 v152, v163, v152
	v_add_f32_e32 v150, 1.0, v150
	v_rcp_f32_e32 v150, v150
	s_nop 0
	v_mul_f32_e32 v150, v151, v150
	v_mul_f32_e32 v150, v155, v150
	v_cvt_pk_bf16_f32 v149, v149, v150
	v_mul_f32_e32 v150, 0xbfb8aa3b, v160
	v_mul_f32_e32 v151, 0xbfb8aa3b, v161
	v_exp_f32_e32 v150, v150
	v_exp_f32_e32 v151, v151
	v_add_f32_e32 v150, 1.0, v150
	v_add_f32_e32 v151, 1.0, v151
	v_rcp_f32_e32 v150, v150
	v_rcp_f32_e32 v151, v151
	v_mul_f32_e32 v150, v160, v150
	v_mul_f32_e32 v151, v161, v151
	v_mul_f32_e32 v150, v164, v150
	v_mul_f32_e32 v151, v165, v151
	v_cvt_pk_bf16_f32 v150, v150, v151
	v_mul_f32_e32 v151, 0xbfb8aa3b, v158
	v_exp_f32_e32 v151, v151
	s_nop 0
	v_add_f32_e32 v151, 1.0, v151
	v_rcp_f32_e32 v151, v151
	s_nop 0
	v_mul_f32_e32 v151, v158, v151
	v_mul_f32_e32 v151, v162, v151
	v_cvt_pk_bf16_f32 v151, v151, v152
	v_mad_i64_i32 v[152:153], s[4:5], v147, s33, v[136:137]
	v_lshl_add_u64 v[152:153], v[152:153], 0, v[138:139]
	global_store_dwordx4 v[152:153], v[148:151], off
	ds_read_b32 v148, v145 offset:576
	v_add_u32_e32 v147, 0x90, v146
	s_waitcnt lgkmcnt(0)
; __device__ __forceinline__ unsigned pk2(float lo, float hi) { unsigned r; asm volatile("v_cvt_pk_bf16_f32 %0, %1, %2" : "=v"(r) : "v"(lo), "v"(hi)); return r; }
; __device__ __forceinline__ float siluf_(float x) { return x * __builtin_amdgcn_rcpf(1.0f + __expf(-x)); }
;     template <int mode> __device__ __forceinline__ void run(const f32x4 (&acc)[2][2][4][2], const Unit& u, int wr, int wc, int fr, int fq, const LAS float* sc) const {
;     ...
; #pragma unroll
;             for (int ai = 0; ai < 2; ++ai)
; #pragma unroll
;                 for (int m = 0; m < 4; ++m) {
;                     const int row = row0 + ai * HALF + m * 16;
;                     const float s = sc[ai * HALF + wr * 64 + m * 16 + fr];
;                     const f32x4 g0 = acc[ai][0][m][0] * s, u0 = acc[ai][1][m][0] * s, g1 = acc[ai][0][m][1] * s, u1 = acc[ai][1][m][1] * s;
;                     u32x4 w;
;                     w.x = pk2(siluf_(g0[0]) * u0[0], siluf_(g0[1]) * u0[1]); w.y = pk2(siluf_(g0[2]) * u0[2], siluf_(g0[3]) * u0[3]);
;                     w.z = pk2(siluf_(g1[0]) * u1[0], siluf_(g1[1]) * u1[1]); w.w = pk2(siluf_(g1[2]) * u1[2], siluf_(g1[3]) * u1[3]);
;                     *(u32x4*)(ob + (size_t)row * FF + col0) = w;
;                 }
	v_pk_mul_f32 v[152:153], v[54:55], v[148:149] op_sel_hi:[1,0]
	v_pk_mul_f32 v[150:151], v[56:57], v[148:149] op_sel_hi:[1,0]
	v_pk_mul_f32 v[154:155], v[24:25], v[148:149] op_sel_hi:[1,0]
	v_pk_mul_f32 v[156:157], v[22:23], v[148:149] op_sel_hi:[1,0]
	v_pk_mul_f32 v[158:159], v[52:53], v[148:149] op_sel_hi:[1,0]
	v_pk_mul_f32 v[160:161], v[50:51], v[148:149] op_sel_hi:[1,0]
	v_pk_mul_f32 v[162:163], v[20:21], v[148:149] op_sel_hi:[1,0]
	v_pk_mul_f32 v[164:165], v[18:19], v[148:149] op_sel_hi:[1,0]
	v_mul_f32_e32 v148, 0xbfb8aa3b, v152
	v_mul_f32_e32 v149, 0xbfb8aa3b, v153
	v_exp_f32_e32 v148, v148
	v_exp_f32_e32 v149, v149
	v_add_f32_e32 v148, 1.0, v148
	v_add_f32_e32 v149, 1.0, v149
	v_rcp_f32_e32 v148, v148
	v_rcp_f32_e32 v149, v149
	v_mul_f32_e32 v148, v152, v148
	v_mul_f32_e32 v149, v153, v149
	v_mul_f32_e32 v148, v156, v148
	v_mul_f32_e32 v149, v157, v149
	v_cvt_pk_bf16_f32 v148, v148, v149
	v_mul_f32_e32 v149, 0xbfb8aa3b, v150
	v_exp_f32_e32 v149, v149
	v_mul_f32_e32 v152, 0xbfb8aa3b, v159
	v_exp_f32_e32 v152, v152
	v_add_f32_e32 v149, 1.0, v149
	v_rcp_f32_e32 v149, v149
	v_add_f32_e32 v152, 1.0, v152
	v_rcp_f32_e32 v152, v152
	v_mul_f32_e32 v149, v150, v149
	v_mul_f32_e32 v150, 0xbfb8aa3b, v151
	v_exp_f32_e32 v150, v150
	v_mul_f32_e32 v149, v154, v149
	v_mul_f32_e32 v152, v159, v152
	v_mul_f32_e32 v152, v163, v152
	v_add_f32_e32 v150, 1.0, v150
	v_rcp_f32_e32 v150, v150
	s_nop 0
	v_mul_f32_e32 v150, v151, v150
	v_mul_f32_e32 v150, v155, v150
	v_cvt_pk_bf16_f32 v149, v149, v150
	v_mul_f32_e32 v150, 0xbfb8aa3b, v160
	v_mul_f32_e32 v151, 0xbfb8aa3b, v161
	v_exp_f32_e32 v150, v150
	v_exp_f32_e32 v151, v151
	v_add_f32_e32 v150, 1.0, v150
	v_add_f32_e32 v151, 1.0, v151
	v_rcp_f32_e32 v150, v150
	v_rcp_f32_e32 v151, v151
	v_mul_f32_e32 v150, v160, v150
	v_mul_f32_e32 v151, v161, v151
	v_mul_f32_e32 v150, v164, v150
	v_mul_f32_e32 v151, v165, v151
	v_cvt_pk_bf16_f32 v150, v150, v151
	v_mul_f32_e32 v151, 0xbfb8aa3b, v158
	v_exp_f32_e32 v151, v151
	s_nop 0
	v_add_f32_e32 v151, 1.0, v151
	v_rcp_f32_e32 v151, v151
	s_nop 0
	v_mul_f32_e32 v151, v158, v151
	v_mul_f32_e32 v151, v162, v151
	v_cvt_pk_bf16_f32 v151, v151, v152
	v_mad_i64_i32 v[152:153], s[4:5], v147, s33, v[136:137]
	v_lshl_add_u64 v[152:153], v[152:153], 0, v[138:139]
	global_store_dwordx4 v[152:153], v[148:151], off
	ds_read_b32 v148, v145 offset:640
	v_add_u32_e32 v147, 0xa0, v146
	s_waitcnt lgkmcnt(0)
	v_pk_mul_f32 v[152:153], v[46:47], v[148:149] op_sel_hi:[1,0]
	v_pk_mul_f32 v[150:151], v[48:49], v[148:149] op_sel_hi:[1,0]
	v_pk_mul_f32 v[154:155], v[16:17], v[148:149] op_sel_hi:[1,0]
	v_pk_mul_f32 v[156:157], v[14:15], v[148:149] op_sel_hi:[1,0]
	v_pk_mul_f32 v[158:159], v[44:45], v[148:149] op_sel_hi:[1,0]
	v_pk_mul_f32 v[160:161], v[42:43], v[148:149] op_sel_hi:[1,0]
	v_pk_mul_f32 v[162:163], v[12:13], v[148:149] op_sel_hi:[1,0]
	v_pk_mul_f32 v[164:165], v[10:11], v[148:149] op_sel_hi:[1,0]
	v_mul_f32_e32 v148, 0xbfb8aa3b, v152
	v_mul_f32_e32 v149, 0xbfb8aa3b, v153
	v_exp_f32_e32 v148, v148
	v_exp_f32_e32 v149, v149
	v_add_f32_e32 v148, 1.0, v148
	v_add_f32_e32 v149, 1.0, v149
	v_rcp_f32_e32 v148, v148
	v_rcp_f32_e32 v149, v149
	v_mul_f32_e32 v148, v152, v148
	v_mul_f32_e32 v149, v153, v149
	v_mul_f32_e32 v148, v156, v148
	v_mul_f32_e32 v149, v157, v149
	v_cvt_pk_bf16_f32 v148, v148, v149
	v_mul_f32_e32 v149, 0xbfb8aa3b, v150
	v_exp_f32_e32 v149, v149
	v_mul_f32_e32 v152, 0xbfb8aa3b, v159
	v_exp_f32_e32 v152, v152
	v_add_f32_e32 v149, 1.0, v149
	v_rcp_f32_e32 v149, v149
	v_add_f32_e32 v152, 1.0, v152
	v_rcp_f32_e32 v152, v152
	v_mul_f32_e32 v149, v150, v149
	v_mul_f32_e32 v150, 0xbfb8aa3b, v151
	v_exp_f32_e32 v150, v150
	v_mul_f32_e32 v149, v154, v149
	v_mul_f32_e32 v152, v159, v152
	v_mul_f32_e32 v152, v163, v152
	v_add_f32_e32 v150, 1.0, v150
	v_rcp_f32_e32 v150, v150
	s_nop 0
	v_mul_f32_e32 v150, v151, v150
	v_mul_f32_e32 v150, v155, v150
	v_cvt_pk_bf16_f32 v149, v149, v150
	v_mul_f32_e32 v150, 0xbfb8aa3b, v160
	v_mul_f32_e32 v151, 0xbfb8aa3b, v161
	v_exp_f32_e32 v150, v150
	v_exp_f32_e32 v151, v151
	v_add_f32_e32 v150, 1.0, v150
	v_add_f32_e32 v151, 1.0, v151
	v_rcp_f32_e32 v150, v150
	v_rcp_f32_e32 v151, v151
	v_mul_f32_e32 v150, v160, v150
	v_mul_f32_e32 v151, v161, v151
	v_mul_f32_e32 v150, v164, v150
	v_mul_f32_e32 v151, v165, v151
	v_cvt_pk_bf16_f32 v150, v150, v151
	v_mul_f32_e32 v151, 0xbfb8aa3b, v158
	v_exp_f32_e32 v151, v151
	v_add_u32_e32 v164, 0xb0, v146
	v_add_f32_e32 v151, 1.0, v151
	v_rcp_f32_e32 v151, v151
	s_nop 0
	v_mul_f32_e32 v151, v158, v151
	v_mul_f32_e32 v151, v162, v151
	v_cvt_pk_bf16_f32 v151, v151, v152
	ds_read_b32 v146, v145 offset:704
	v_mad_i64_i32 v[152:153], s[4:5], v147, s33, v[136:137]
	v_lshl_add_u64 v[152:153], v[152:153], 0, v[138:139]
	global_store_dwordx4 v[152:153], v[148:151], off
	s_waitcnt lgkmcnt(0)
; __device__ __forceinline__ unsigned pk2(float lo, float hi) { unsigned r; asm volatile("v_cvt_pk_bf16_f32 %0, %1, %2" : "=v"(r) : "v"(lo), "v"(hi)); return r; }
; __device__ __forceinline__ float siluf_(float x) { return x * __builtin_amdgcn_rcpf(1.0f + __expf(-x)); }
;     template <int mode> __device__ __forceinline__ void run(const f32x4 (&acc)[2][2][4][2], const Unit& u, int wr, int wc, int fr, int fq, const LAS float* sc) const {
;     ...
; #pragma unroll
;             for (int ai = 0; ai < 2; ++ai)
; #pragma unroll
;                 for (int m = 0; m < 4; ++m) {
;                     const int row = row0 + ai * HALF + m * 16;
;                     const float s = sc[ai * HALF + wr * 64 + m * 16 + fr];
;                     const f32x4 g0 = acc[ai][0][m][0] * s, u0 = acc[ai][1][m][0] * s, g1 = acc[ai][0][m][1] * s, u1 = acc[ai][1][m][1] * s;
;                     u32x4 w;
;                     w.x = pk2(siluf_(g0[0]) * u0[0], siluf_(g0[1]) * u0[1]); w.y = pk2(siluf_(g0[2]) * u0[2], siluf_(g0[3]) * u0[3]);
;                     w.z = pk2(siluf_(g1[0]) * u1[0], siluf_(g1[1]) * u1[1]); w.w = pk2(siluf_(g1[2]) * u1[2], siluf_(g1[3]) * u1[3]);
;                     *(u32x4*)(ob + (size_t)row * FF + col0) = w;
;                 }
; template <int MODE, class EpiT, class Sched>
; __device__ __forceinline__ void gemm_phase(LAS unsigned char* lds, const Gemm g, const Sched& S, const EpiT& E) {
;     ...
;         if (!has_next) break;
; #pragma unroll
;         for (int a = 0; a < 2; ++a)
; #pragma unroll
;             for (int b = 0; b < 2; ++b)
; #pragma unroll
;                 for (int m = 0; m < 4; ++m)
; #pragma unroll
;                     for (int n = 0; n < 2; ++n) acc[a][b][m][n] = (f32x4){0.f, 0.f, 0.f, 0.f};
;         cur = nxt; cA = nA; cB = nB; ++ui;
	v_pk_mul_f32 v[152:153], v[8:9], v[146:147] op_sel_hi:[1,0]
	v_pk_mul_f32 v[154:155], v[6:7], v[146:147] op_sel_hi:[1,0]
	v_pk_mul_f32 v[150:151], v[38:39], v[146:147] op_sel_hi:[1,0]
	v_pk_mul_f32 v[148:149], v[40:41], v[146:147] op_sel_hi:[1,0]
	v_pk_mul_f32 v[156:157], v[36:37], v[146:147] op_sel_hi:[1,0]
	v_pk_mul_f32 v[158:159], v[34:35], v[146:147] op_sel_hi:[1,0]
	v_pk_mul_f32 v[160:161], v[4:5], v[146:147] op_sel_hi:[1,0]
	v_pk_mul_f32 v[162:163], v[2:3], v[146:147] op_sel_hi:[1,0]
	v_mul_f32_e32 v145, 0xbfb8aa3b, v150
	v_mul_f32_e32 v146, 0xbfb8aa3b, v151
	v_exp_f32_e32 v145, v145
	v_exp_f32_e32 v146, v146
	v_mul_f32_e32 v147, 0xbfb8aa3b, v149
	v_exp_f32_e32 v147, v147
	v_add_f32_e32 v145, 1.0, v145
	v_add_f32_e32 v146, 1.0, v146
	v_rcp_f32_e32 v145, v145
	v_rcp_f32_e32 v146, v146
	v_add_f32_e32 v147, 1.0, v147
	v_rcp_f32_e32 v147, v147
	v_mul_f32_e32 v145, v150, v145
	v_mul_f32_e32 v146, v151, v146
	v_mul_f32_e32 v145, v154, v145
	v_mul_f32_e32 v146, v155, v146
	v_cvt_pk_bf16_f32 v146, v145, v146
	v_mul_f32_e32 v145, 0xbfb8aa3b, v148
	v_exp_f32_e32 v145, v145
	v_mul_f32_e32 v147, v149, v147
	v_mul_f32_e32 v147, v153, v147
	v_mul_f32_e32 v149, 0xbfb8aa3b, v157
	v_add_f32_e32 v145, 1.0, v145
	v_rcp_f32_e32 v145, v145
	v_exp_f32_e32 v149, v149
	v_mad_i64_i32 v[136:137], s[4:5], v164, s33, v[136:137]
	v_mul_f32_e32 v145, v148, v145
	v_mul_f32_e32 v145, v152, v145
	v_cvt_pk_bf16_f32 v147, v145, v147
	v_mul_f32_e32 v145, 0xbfb8aa3b, v158
	v_mul_f32_e32 v148, 0xbfb8aa3b, v159
	v_exp_f32_e32 v145, v145
	v_exp_f32_e32 v148, v148
	v_add_f32_e32 v149, 1.0, v149
	v_rcp_f32_e32 v149, v149
	v_add_f32_e32 v145, 1.0, v145
	v_add_f32_e32 v148, 1.0, v148
	v_rcp_f32_e32 v145, v145
	v_rcp_f32_e32 v148, v148
	v_mul_f32_e32 v149, v157, v149
	v_mul_f32_e32 v149, v161, v149
	v_mul_f32_e32 v145, v158, v145
	v_mul_f32_e32 v148, v159, v148
	v_mul_f32_e32 v145, v162, v145
	v_mul_f32_e32 v148, v163, v148
	v_cvt_pk_bf16_f32 v148, v145, v148
	v_mul_f32_e32 v145, 0xbfb8aa3b, v156
	v_exp_f32_e32 v145, v145
	v_lshl_add_u64 v[136:137], v[136:137], 0, v[138:139]
	v_add_f32_e32 v145, 1.0, v145
	v_rcp_f32_e32 v145, v145
	s_nop 0
	v_mul_f32_e32 v145, v156, v145
	v_mul_f32_e32 v145, v160, v145
	v_cvt_pk_bf16_f32 v149, v145, v149
	global_store_dwordx4 v[136:137], v[146:149], off
	s_cbranch_vccnz .LBB0_324
	v_mov_b32_e32 v2, 0
	s_mov_b32 s9, s61
	s_mov_b32 s8, s60
	s_mov_b64 s[12:13], s[28:29]
	s_mov_b64 s[10:11], s[34:35]
	s_mov_b32 s57, s2
	v_mov_b32_e32 v3, v2
	v_mov_b32_e32 v4, v2
	v_mov_b32_e32 v5, v2
	v_mov_b32_e32 v6, v2
	v_mov_b32_e32 v7, v2
	v_mov_b32_e32 v8, v2
	v_mov_b32_e32 v9, v2
	v_mov_b32_e32 v10, v2
	v_mov_b32_e32 v11, v2
	v_mov_b32_e32 v12, v2
	v_mov_b32_e32 v13, v2
	v_mov_b32_e32 v14, v2
	v_mov_b32_e32 v15, v2
	v_mov_b32_e32 v16, v2
	v_mov_b32_e32 v17, v2
	v_mov_b32_e32 v18, v2
	v_mov_b32_e32 v19, v2
	v_mov_b32_e32 v20, v2
	v_mov_b32_e32 v21, v2
	v_mov_b32_e32 v22, v2
	v_mov_b32_e32 v23, v2
	v_mov_b32_e32 v24, v2
	v_mov_b32_e32 v25, v2
	v_mov_b32_e32 v26, v2
	v_mov_b32_e32 v27, v2
	v_mov_b32_e32 v28, v2
	v_mov_b32_e32 v29, v2
	v_mov_b32_e32 v30, v2
	v_mov_b32_e32 v31, v2
	v_mov_b32_e32 v32, v2
	v_mov_b32_e32 v33, v2
	v_mov_b32_e32 v34, v2
	v_mov_b32_e32 v35, v2
	v_mov_b32_e32 v36, v2
	v_mov_b32_e32 v37, v2
	v_mov_b32_e32 v38, v2
	v_mov_b32_e32 v39, v2
	v_mov_b32_e32 v40, v2
	v_mov_b32_e32 v41, v2
	v_mov_b32_e32 v42, v2
	v_mov_b32_e32 v43, v2
	v_mov_b32_e32 v44, v2
	v_mov_b32_e32 v45, v2
	v_mov_b32_e32 v46, v2
	v_mov_b32_e32 v47, v2
	v_mov_b32_e32 v48, v2
	v_mov_b32_e32 v49, v2
	v_mov_b32_e32 v50, v2
	v_mov_b32_e32 v51, v2
	v_mov_b32_e32 v52, v2
	v_mov_b32_e32 v53, v2
	v_mov_b32_e32 v54, v2
	v_mov_b32_e32 v55, v2
	v_mov_b32_e32 v56, v2
	v_mov_b32_e32 v57, v2
	v_mov_b32_e32 v58, v2
	v_mov_b32_e32 v59, v2
	v_mov_b32_e32 v60, v2
	v_mov_b32_e32 v61, v2
	v_mov_b32_e32 v62, v2
	v_mov_b32_e32 v63, v2
	v_mov_b32_e32 v64, v2
	v_mov_b32_e32 v65, v2
	v_mov_b32_e32 v66, v2
	v_mov_b32_e32 v67, v2
	v_mov_b32_e32 v68, v2
	v_mov_b32_e32 v69, v2
	v_mov_b32_e32 v70, v2
	v_mov_b32_e32 v71, v2
	v_mov_b32_e32 v72, v2
	v_mov_b32_e32 v73, v2
	v_mov_b32_e32 v74, v2
	v_mov_b32_e32 v75, v2
	v_mov_b32_e32 v76, v2
	v_mov_b32_e32 v77, v2
	v_mov_b32_e32 v78, v2
	v_mov_b32_e32 v79, v2
	v_mov_b32_e32 v80, v2
	v_mov_b32_e32 v81, v2
	v_mov_b32_e32 v82, v2
	v_mov_b32_e32 v83, v2
	v_mov_b32_e32 v84, v2
	v_mov_b32_e32 v85, v2
	v_mov_b32_e32 v86, v2
	v_mov_b32_e32 v87, v2
	v_mov_b32_e32 v88, v2
	v_mov_b32_e32 v89, v2
	v_mov_b32_e32 v90, v2
	v_mov_b32_e32 v91, v2
	v_mov_b32_e32 v92, v2
	v_mov_b32_e32 v93, v2
	v_mov_b32_e32 v94, v2
	v_mov_b32_e32 v95, v2
	v_mov_b32_e32 v96, v2
	v_mov_b32_e32 v97, v2
	v_mov_b32_e32 v98, v2
	v_mov_b32_e32 v99, v2
	v_mov_b32_e32 v100, v2
	v_mov_b32_e32 v101, v2
	v_mov_b32_e32 v102, v2
	v_mov_b32_e32 v103, v2
	v_mov_b32_e32 v104, v2
	v_mov_b32_e32 v105, v2
	v_mov_b32_e32 v106, v2
	v_mov_b32_e32 v107, v2
	v_mov_b32_e32 v108, v2
	v_mov_b32_e32 v109, v2
	v_mov_b32_e32 v110, v2
	v_mov_b32_e32 v111, v2
	v_mov_b32_e32 v112, v2
	v_mov_b32_e32 v113, v2
	v_mov_b32_e32 v114, v2
	v_mov_b32_e32 v115, v2
	v_mov_b32_e32 v116, v2
	v_mov_b32_e32 v117, v2
	v_mov_b32_e32 v118, v2
	v_mov_b32_e32 v119, v2
	v_mov_b32_e32 v120, v2
	v_mov_b32_e32 v121, v2
	v_mov_b32_e32 v122, v2
	v_mov_b32_e32 v123, v2
	v_mov_b32_e32 v124, v2
	v_mov_b32_e32 v125, v2
	v_mov_b32_e32 v126, v2
	v_mov_b32_e32 v127, v2
	v_mov_b32_e32 v128, v2
	v_mov_b32_e32 v129, v2
	s_branch .LBB0_324
